# k15b + packed-f32 EpiRes epilogues (P2/P5/P7) + sc1 write-through on the EpiAct ACT stores
# speedup vs baseline: 1.0012x; 1.0012x over previous
; __device__ __forceinline__ unsigned cvt_pk_bf16(float lo, float hi) { unsigned r; asm volatile("v_cvt_pk_bf16_f32 %0, %1, %2" : "=v"(r) : "v"(lo), "v"(hi)); return r; }
; __device__ __forceinline__ float fast_rcp(float x) { return __builtin_amdgcn_rcpf(x); }
; __device__ __forceinline__ unsigned cvt_pk_bf16(float lo, float hi) { const f32x2 v = {lo, hi}; const bf16x2_t b = __builtin_convertvector(v, bf16x2_t); return __builtin_bit_cast(unsigned, b); }
;     __device__ __forceinline__ void operator()(const f32x4 (&acc)[2][2][4][2], const Unit& u, int wr, int wc, int fr, int fq) const {
;         const int row0 = u.pm * BM + wr * 64 + fr, col0 = u.pn * HALF + wc * 32 + 8 * fq;
;         float rsv[2][4]; row_rs8(SS, row0, fq, rsv);
; #pragma unroll
;         for (int ai = 0; ai < 2; ++ai)
; #pragma unroll
;             for (int m = 0; m < 4; ++m) {
;                 const int r = row0 + ai * HALF + m * 16; const float rs = rsv[ai][m], nrs = rs * -1.4426950408889634f, rs2 = rs * rs;
;                 float o[8];
; #pragma unroll
;                 for (int n = 0; n < 2; ++n) {
;                     const f32x4 t = acc[ai][0][m][n] * nrs, p = (acc[ai][0][m][n] * acc[ai][1][m][n]) * rs2;
; #pragma unroll
;                     for (int j = 0; j < 4; ++j) o[4 * n + j] = p[j] * fast_rcp(1.0f + __builtin_amdgcn_exp2f(t[j]));
;                 }
;                 u32x4 w; w.x = cvt_pk_bf16(o[0], o[1]); w.y = cvt_pk_bf16(o[2], o[3]); w.z = cvt_pk_bf16(o[4], o[5]); w.w = cvt_pk_bf16(o[6], o[7]);
;                 *(u32x4*)(O + (size_t)r * ldo + col0) = w;
;             }
.Lrs_reuse_p1:
	v_pk_mul_f32 v[124:125], v[124:125], v[120:121]
	v_pk_mul_f32 v[126:127], v[126:127], v[122:123]
	v_pk_mul_f32 v[112:113], v[112:113], v[116:117]
	v_pk_mul_f32 v[114:115], v[114:115], v[118:119]
	v_pk_mul_f32 v[104:105], v[104:105], v[108:109]
	v_pk_mul_f32 v[106:107], v[106:107], v[110:111]
	v_pk_mul_f32 v[96:97], v[96:97], v[100:101]
	v_pk_mul_f32 v[98:99], v[98:99], v[102:103]
	v_pk_mul_f32 v[88:89], v[88:89], v[92:93]
	v_pk_mul_f32 v[90:91], v[90:91], v[94:95]
	v_pk_mul_f32 v[80:81], v[80:81], v[84:85]
	v_pk_mul_f32 v[82:83], v[82:83], v[86:87]
	v_pk_mul_f32 v[72:73], v[72:73], v[76:77]
	v_pk_mul_f32 v[74:75], v[74:75], v[78:79]
	v_pk_mul_f32 v[64:65], v[64:65], v[68:69]
	v_pk_mul_f32 v[66:67], v[66:67], v[70:71]
	v_pk_mul_f32 v[56:57], v[56:57], v[60:61]
	v_pk_mul_f32 v[58:59], v[58:59], v[62:63]
	v_pk_mul_f32 v[48:49], v[48:49], v[52:53]
	v_pk_mul_f32 v[50:51], v[50:51], v[54:55]
	v_pk_mul_f32 v[40:41], v[40:41], v[44:45]
	v_pk_mul_f32 v[42:43], v[42:43], v[46:47]
	v_pk_mul_f32 v[32:33], v[32:33], v[36:37]
	v_pk_mul_f32 v[34:35], v[34:35], v[38:39]
	v_pk_mul_f32 v[24:25], v[24:25], v[28:29]
	v_pk_mul_f32 v[26:27], v[26:27], v[30:31]
	v_pk_mul_f32 v[16:17], v[16:17], v[20:21]
	v_pk_mul_f32 v[18:19], v[18:19], v[22:23]
	v_pk_mul_f32 v[8:9], v[8:9], v[12:13]
	v_pk_mul_f32 v[10:11], v[10:11], v[14:15]
	v_pk_mul_f32 v[0:1], v[0:1], v[4:5]
	v_pk_mul_f32 v[2:3], v[2:3], v[6:7]
	v_mul_f32_e32 v230, 0xbfb8aa3b, v242
	v_mul_f32_e32 v231, v242, v242
	v_mul_f32_e32 v232, 0xbfb8aa3b, v243
	v_mul_f32_e32 v233, v243, v243
	v_mul_f32_e32 v234, 0xbfb8aa3b, v244
	v_mul_f32_e32 v235, v244, v244
	v_mul_f32_e32 v184, 0xbfb8aa3b, v245
	v_mul_f32_e32 v185, v245, v245
	v_mul_f32_e32 v186, 0xbfb8aa3b, v246
	v_mul_f32_e32 v187, v246, v246
	v_mul_f32_e32 v188, 0xbfb8aa3b, v247
	v_mul_f32_e32 v189, v247, v247
	v_mul_f32_e32 v190, 0xbfb8aa3b, v248
	v_mul_f32_e32 v191, v248, v248
	v_mul_f32_e32 v204, 0xbfb8aa3b, v249
	v_mul_f32_e32 v205, v249, v249
	v_pk_mul_f32 v[120:121], v[120:121], v[230:231] op_sel_hi:[1,0]
	v_pk_mul_f32 v[122:123], v[122:123], v[230:231] op_sel_hi:[1,0]
	v_pk_mul_f32 v[116:117], v[116:117], v[230:231] op_sel_hi:[1,0]
	v_pk_mul_f32 v[118:119], v[118:119], v[230:231] op_sel_hi:[1,0]
	v_exp_f32_e32 v120, v120
	v_exp_f32_e32 v121, v121
	v_exp_f32_e32 v122, v122
	v_exp_f32_e32 v123, v123
	v_exp_f32_e32 v116, v116
	v_exp_f32_e32 v117, v117
	v_exp_f32_e32 v118, v118
	v_exp_f32_e32 v119, v119
	v_pk_mul_f32 v[124:125], v[124:125], v[230:231] op_sel:[0,1] op_sel_hi:[1,1]
	v_pk_mul_f32 v[126:127], v[126:127], v[230:231] op_sel:[0,1] op_sel_hi:[1,1]
	v_pk_mul_f32 v[112:113], v[112:113], v[230:231] op_sel:[0,1] op_sel_hi:[1,1]
	v_pk_mul_f32 v[114:115], v[114:115], v[230:231] op_sel:[0,1] op_sel_hi:[1,1]
	v_pk_add_f32 v[120:121], v[120:121], 1.0 op_sel_hi:[1,0]
	v_pk_add_f32 v[122:123], v[122:123], 1.0 op_sel_hi:[1,0]
	v_pk_add_f32 v[116:117], v[116:117], 1.0 op_sel_hi:[1,0]
	v_pk_add_f32 v[118:119], v[118:119], 1.0 op_sel_hi:[1,0]
	v_rcp_f32_e32 v120, v120
	v_rcp_f32_e32 v121, v121
	v_rcp_f32_e32 v122, v122
	v_rcp_f32_e32 v123, v123
	v_rcp_f32_e32 v116, v116
	v_rcp_f32_e32 v117, v117
	v_rcp_f32_e32 v118, v118
	v_rcp_f32_e32 v119, v119
	v_mad_i64_i32 v[208:209], s[4:5], v162, s68, v[220:221]
	v_lshl_add_u64 v[208:209], v[208:209], 0, v[250:251]
	v_pk_mul_f32 v[124:125], v[124:125], v[120:121]
	v_pk_mul_f32 v[126:127], v[126:127], v[122:123]
	v_pk_mul_f32 v[112:113], v[112:113], v[116:117]
	v_pk_mul_f32 v[114:115], v[114:115], v[118:119]
	v_cvt_pk_bf16_f32 v120, v124, v125
	v_cvt_pk_bf16_f32 v121, v126, v127
	v_cvt_pk_bf16_f32 v122, v112, v113
	v_cvt_pk_bf16_f32 v123, v114, v115
	global_store_dwordx4 v[208:209], v[120:123], off sc1
	v_pk_mul_f32 v[108:109], v[108:109], v[232:233] op_sel_hi:[1,0]
	v_pk_mul_f32 v[110:111], v[110:111], v[232:233] op_sel_hi:[1,0]
	v_pk_mul_f32 v[100:101], v[100:101], v[232:233] op_sel_hi:[1,0]
	v_pk_mul_f32 v[102:103], v[102:103], v[232:233] op_sel_hi:[1,0]
	v_exp_f32_e32 v108, v108
	v_exp_f32_e32 v109, v109
	v_exp_f32_e32 v110, v110
	v_exp_f32_e32 v111, v111
	v_exp_f32_e32 v100, v100
	v_exp_f32_e32 v101, v101
	v_exp_f32_e32 v102, v102
	v_exp_f32_e32 v103, v103
	v_pk_mul_f32 v[104:105], v[104:105], v[232:233] op_sel:[0,1] op_sel_hi:[1,1]
	v_pk_mul_f32 v[106:107], v[106:107], v[232:233] op_sel:[0,1] op_sel_hi:[1,1]
	v_pk_mul_f32 v[96:97], v[96:97], v[232:233] op_sel:[0,1] op_sel_hi:[1,1]
	v_pk_mul_f32 v[98:99], v[98:99], v[232:233] op_sel:[0,1] op_sel_hi:[1,1]
	v_pk_add_f32 v[108:109], v[108:109], 1.0 op_sel_hi:[1,0]
	v_pk_add_f32 v[110:111], v[110:111], 1.0 op_sel_hi:[1,0]
	v_pk_add_f32 v[100:101], v[100:101], 1.0 op_sel_hi:[1,0]
	v_pk_add_f32 v[102:103], v[102:103], 1.0 op_sel_hi:[1,0]
	v_rcp_f32_e32 v108, v108
	v_rcp_f32_e32 v109, v109
	v_rcp_f32_e32 v110, v110
	v_rcp_f32_e32 v111, v111
	v_rcp_f32_e32 v100, v100
	v_rcp_f32_e32 v101, v101
	v_rcp_f32_e32 v102, v102
	v_rcp_f32_e32 v103, v103
	v_mad_i64_i32 v[208:209], s[4:5], v160, s68, v[220:221]
	v_lshl_add_u64 v[208:209], v[208:209], 0, v[250:251]
	v_pk_mul_f32 v[104:105], v[104:105], v[108:109]
	v_pk_mul_f32 v[106:107], v[106:107], v[110:111]
	v_pk_mul_f32 v[96:97], v[96:97], v[100:101]
	v_pk_mul_f32 v[98:99], v[98:99], v[102:103]
	v_cvt_pk_bf16_f32 v108, v104, v105
	v_cvt_pk_bf16_f32 v109, v106, v107
	v_cvt_pk_bf16_f32 v110, v96, v97
	v_cvt_pk_bf16_f32 v111, v98, v99
	global_store_dwordx4 v[208:209], v[108:111], off sc1
	v_pk_mul_f32 v[92:93], v[92:93], v[234:235] op_sel_hi:[1,0]
	v_pk_mul_f32 v[94:95], v[94:95], v[234:235] op_sel_hi:[1,0]
	v_pk_mul_f32 v[84:85], v[84:85], v[234:235] op_sel_hi:[1,0]
	v_pk_mul_f32 v[86:87], v[86:87], v[234:235] op_sel_hi:[1,0]
; __device__ __forceinline__ unsigned cvt_pk_bf16(float lo, float hi) { unsigned r; asm volatile("v_cvt_pk_bf16_f32 %0, %1, %2" : "=v"(r) : "v"(lo), "v"(hi)); return r; }
; __device__ __forceinline__ float fast_rcp(float x) { return __builtin_amdgcn_rcpf(x); }
; __device__ __forceinline__ unsigned cvt_pk_bf16(float lo, float hi) { const f32x2 v = {lo, hi}; const bf16x2_t b = __builtin_convertvector(v, bf16x2_t); return __builtin_bit_cast(unsigned, b); }
;     __device__ __forceinline__ void operator()(const f32x4 (&acc)[2][2][4][2], const Unit& u, int wr, int wc, int fr, int fq) const {
;         const int row0 = u.pm * BM + wr * 64 + fr, col0 = u.pn * HALF + wc * 32 + 8 * fq;
;         float rsv[2][4]; row_rs8(SS, row0, fq, rsv);
; #pragma unroll
;         for (int ai = 0; ai < 2; ++ai)
; #pragma unroll
;             for (int m = 0; m < 4; ++m) {
;                 const int r = row0 + ai * HALF + m * 16; const float rs = rsv[ai][m], nrs = rs * -1.4426950408889634f, rs2 = rs * rs;
;                 float o[8];
; #pragma unroll
;                 for (int n = 0; n < 2; ++n) {
;                     const f32x4 t = acc[ai][0][m][n] * nrs, p = (acc[ai][0][m][n] * acc[ai][1][m][n]) * rs2;
; #pragma unroll
;                     for (int j = 0; j < 4; ++j) o[4 * n + j] = p[j] * fast_rcp(1.0f + __builtin_amdgcn_exp2f(t[j]));
;                 }
;                 u32x4 w; w.x = cvt_pk_bf16(o[0], o[1]); w.y = cvt_pk_bf16(o[2], o[3]); w.z = cvt_pk_bf16(o[4], o[5]); w.w = cvt_pk_bf16(o[6], o[7]);
;                 *(u32x4*)(O + (size_t)r * ldo + col0) = w;
;             }
	v_exp_f32_e32 v92, v92
	v_exp_f32_e32 v93, v93
	v_exp_f32_e32 v94, v94
	v_exp_f32_e32 v95, v95
	v_exp_f32_e32 v84, v84
	v_exp_f32_e32 v85, v85
	v_exp_f32_e32 v86, v86
	v_exp_f32_e32 v87, v87
	v_pk_mul_f32 v[88:89], v[88:89], v[234:235] op_sel:[0,1] op_sel_hi:[1,1]
	v_pk_mul_f32 v[90:91], v[90:91], v[234:235] op_sel:[0,1] op_sel_hi:[1,1]
	v_pk_mul_f32 v[80:81], v[80:81], v[234:235] op_sel:[0,1] op_sel_hi:[1,1]
	v_pk_mul_f32 v[82:83], v[82:83], v[234:235] op_sel:[0,1] op_sel_hi:[1,1]
	v_pk_add_f32 v[92:93], v[92:93], 1.0 op_sel_hi:[1,0]
	v_pk_add_f32 v[94:95], v[94:95], 1.0 op_sel_hi:[1,0]
	v_pk_add_f32 v[84:85], v[84:85], 1.0 op_sel_hi:[1,0]
	v_pk_add_f32 v[86:87], v[86:87], 1.0 op_sel_hi:[1,0]
	v_rcp_f32_e32 v92, v92
	v_rcp_f32_e32 v93, v93
	v_rcp_f32_e32 v94, v94
	v_rcp_f32_e32 v95, v95
	v_rcp_f32_e32 v84, v84
	v_rcp_f32_e32 v85, v85
	v_rcp_f32_e32 v86, v86
	v_rcp_f32_e32 v87, v87
	v_mad_i64_i32 v[208:209], s[4:5], v158, s68, v[220:221]
	v_lshl_add_u64 v[208:209], v[208:209], 0, v[250:251]
	v_pk_mul_f32 v[88:89], v[88:89], v[92:93]
	v_pk_mul_f32 v[90:91], v[90:91], v[94:95]
	v_pk_mul_f32 v[80:81], v[80:81], v[84:85]
	v_pk_mul_f32 v[82:83], v[82:83], v[86:87]
	v_cvt_pk_bf16_f32 v92, v88, v89
	v_cvt_pk_bf16_f32 v93, v90, v91
	v_cvt_pk_bf16_f32 v94, v80, v81
	v_cvt_pk_bf16_f32 v95, v82, v83
	global_store_dwordx4 v[208:209], v[92:95], off sc1
	v_pk_mul_f32 v[76:77], v[76:77], v[184:185] op_sel_hi:[1,0]
	v_pk_mul_f32 v[78:79], v[78:79], v[184:185] op_sel_hi:[1,0]
	v_pk_mul_f32 v[68:69], v[68:69], v[184:185] op_sel_hi:[1,0]
	v_pk_mul_f32 v[70:71], v[70:71], v[184:185] op_sel_hi:[1,0]
	v_exp_f32_e32 v76, v76
	v_exp_f32_e32 v77, v77
	v_exp_f32_e32 v78, v78
	v_exp_f32_e32 v79, v79
	v_exp_f32_e32 v68, v68
	v_exp_f32_e32 v69, v69
	v_exp_f32_e32 v70, v70
	v_exp_f32_e32 v71, v71
	v_pk_mul_f32 v[72:73], v[72:73], v[184:185] op_sel:[0,1] op_sel_hi:[1,1]
	v_pk_mul_f32 v[74:75], v[74:75], v[184:185] op_sel:[0,1] op_sel_hi:[1,1]
	v_pk_mul_f32 v[64:65], v[64:65], v[184:185] op_sel:[0,1] op_sel_hi:[1,1]
	v_pk_mul_f32 v[66:67], v[66:67], v[184:185] op_sel:[0,1] op_sel_hi:[1,1]
	v_pk_add_f32 v[76:77], v[76:77], 1.0 op_sel_hi:[1,0]
	v_pk_add_f32 v[78:79], v[78:79], 1.0 op_sel_hi:[1,0]
	v_pk_add_f32 v[68:69], v[68:69], 1.0 op_sel_hi:[1,0]
	v_pk_add_f32 v[70:71], v[70:71], 1.0 op_sel_hi:[1,0]
	v_rcp_f32_e32 v76, v76
	v_rcp_f32_e32 v77, v77
	v_rcp_f32_e32 v78, v78
	v_rcp_f32_e32 v79, v79
	v_rcp_f32_e32 v68, v68
	v_rcp_f32_e32 v69, v69
	v_rcp_f32_e32 v70, v70
	v_rcp_f32_e32 v71, v71
	v_mad_i64_i32 v[208:209], s[4:5], v156, s68, v[220:221]
	v_lshl_add_u64 v[208:209], v[208:209], 0, v[250:251]
	v_pk_mul_f32 v[72:73], v[72:73], v[76:77]
	v_pk_mul_f32 v[74:75], v[74:75], v[78:79]
	v_pk_mul_f32 v[64:65], v[64:65], v[68:69]
	v_pk_mul_f32 v[66:67], v[66:67], v[70:71]
	v_cvt_pk_bf16_f32 v76, v72, v73
	v_cvt_pk_bf16_f32 v77, v74, v75
	v_cvt_pk_bf16_f32 v78, v64, v65
	v_cvt_pk_bf16_f32 v79, v66, v67
	global_store_dwordx4 v[208:209], v[76:79], off sc1
	v_pk_mul_f32 v[60:61], v[60:61], v[186:187] op_sel_hi:[1,0]
	v_pk_mul_f32 v[62:63], v[62:63], v[186:187] op_sel_hi:[1,0]
	v_pk_mul_f32 v[52:53], v[52:53], v[186:187] op_sel_hi:[1,0]
	v_pk_mul_f32 v[54:55], v[54:55], v[186:187] op_sel_hi:[1,0]
	v_exp_f32_e32 v60, v60
	v_exp_f32_e32 v61, v61
	v_exp_f32_e32 v62, v62
	v_exp_f32_e32 v63, v63
	v_exp_f32_e32 v52, v52
	v_exp_f32_e32 v53, v53
	v_exp_f32_e32 v54, v54
	v_exp_f32_e32 v55, v55
	v_pk_mul_f32 v[56:57], v[56:57], v[186:187] op_sel:[0,1] op_sel_hi:[1,1]
	v_pk_mul_f32 v[58:59], v[58:59], v[186:187] op_sel:[0,1] op_sel_hi:[1,1]
	v_pk_mul_f32 v[48:49], v[48:49], v[186:187] op_sel:[0,1] op_sel_hi:[1,1]
	v_pk_mul_f32 v[50:51], v[50:51], v[186:187] op_sel:[0,1] op_sel_hi:[1,1]
	v_pk_add_f32 v[60:61], v[60:61], 1.0 op_sel_hi:[1,0]
	v_pk_add_f32 v[62:63], v[62:63], 1.0 op_sel_hi:[1,0]
	v_pk_add_f32 v[52:53], v[52:53], 1.0 op_sel_hi:[1,0]
	v_pk_add_f32 v[54:55], v[54:55], 1.0 op_sel_hi:[1,0]
	v_rcp_f32_e32 v60, v60
	v_rcp_f32_e32 v61, v61
	v_rcp_f32_e32 v62, v62
	v_rcp_f32_e32 v63, v63
	v_rcp_f32_e32 v52, v52
	v_rcp_f32_e32 v53, v53
	v_rcp_f32_e32 v54, v54
	v_rcp_f32_e32 v55, v55
	v_mad_i64_i32 v[208:209], s[4:5], v154, s68, v[220:221]
	v_lshl_add_u64 v[208:209], v[208:209], 0, v[250:251]
	v_pk_mul_f32 v[56:57], v[56:57], v[60:61]
	v_pk_mul_f32 v[58:59], v[58:59], v[62:63]
	v_pk_mul_f32 v[48:49], v[48:49], v[52:53]
	v_pk_mul_f32 v[50:51], v[50:51], v[54:55]
	v_cvt_pk_bf16_f32 v60, v56, v57
	v_cvt_pk_bf16_f32 v61, v58, v59
	v_cvt_pk_bf16_f32 v62, v48, v49
	v_cvt_pk_bf16_f32 v63, v50, v51
	global_store_dwordx4 v[208:209], v[60:63], off sc1
	v_pk_mul_f32 v[44:45], v[44:45], v[188:189] op_sel_hi:[1,0]
	v_pk_mul_f32 v[46:47], v[46:47], v[188:189] op_sel_hi:[1,0]
; __device__ __forceinline__ unsigned cvt_pk_bf16(float lo, float hi) { unsigned r; asm volatile("v_cvt_pk_bf16_f32 %0, %1, %2" : "=v"(r) : "v"(lo), "v"(hi)); return r; }
; __device__ __forceinline__ float fast_rcp(float x) { return __builtin_amdgcn_rcpf(x); }
; #define PG8_BAR __builtin_amdgcn_s_barrier()
; __device__ __forceinline__ unsigned cvt_pk_bf16(float lo, float hi) { const f32x2 v = {lo, hi}; const bf16x2_t b = __builtin_convertvector(v, bf16x2_t); return __builtin_bit_cast(unsigned, b); }
;     __device__ __forceinline__ void operator()(const f32x4 (&acc)[2][2][4][2], const Unit& u, int wr, int wc, int fr, int fq) const {
;         const int row0 = u.pm * BM + wr * 64 + fr, col0 = u.pn * HALF + wc * 32 + 8 * fq;
;         float rsv[2][4]; row_rs8(SS, row0, fq, rsv);
; #pragma unroll
;         for (int ai = 0; ai < 2; ++ai)
; #pragma unroll
;             for (int m = 0; m < 4; ++m) {
;                 const int r = row0 + ai * HALF + m * 16; const float rs = rsv[ai][m], nrs = rs * -1.4426950408889634f, rs2 = rs * rs;
;                 float o[8];
; #pragma unroll
;                 for (int n = 0; n < 2; ++n) {
;                     const f32x4 t = acc[ai][0][m][n] * nrs, p = (acc[ai][0][m][n] * acc[ai][1][m][n]) * rs2;
; #pragma unroll
;                     for (int j = 0; j < 4; ++j) o[4 * n + j] = p[j] * fast_rcp(1.0f + __builtin_amdgcn_exp2f(t[j]));
;                 }
;                 u32x4 w; w.x = cvt_pk_bf16(o[0], o[1]); w.y = cvt_pk_bf16(o[2], o[3]); w.z = cvt_pk_bf16(o[4], o[5]); w.w = cvt_pk_bf16(o[6], o[7]);
;                 *(u32x4*)(O + (size_t)r * ldo + col0) = w;
;             }
; template <class Epi, class Sched, bool ALIGN_EPI = false, bool SP2 = false>
; __device__ __forceinline__ void gemm_phase(PG8_LAS unsigned char* lds, const Gemm g, const Sched& S, const Epi& E) {
;     ...
;         if (!has_next) break;
; #pragma unroll
;         for (int a = 0; a < 2; ++a)
; #pragma unroll
;             for (int b = 0; b < 2; ++b)
; #pragma unroll
;                 for (int m = 0; m < 4; ++m)
; #pragma unroll
;                     for (int n = 0; n < 2; ++n) acc[a][b][m][n] = (f32x4){0.f, 0.f, 0.f, 0.f};
;         cur = nxt; cA = nA; cB = nB; ++ui;
;         if constexpr (ALIGN_EPI) { if (wr == 1) PG8_BAR; }
	v_pk_mul_f32 v[36:37], v[36:37], v[188:189] op_sel_hi:[1,0]
	v_pk_mul_f32 v[38:39], v[38:39], v[188:189] op_sel_hi:[1,0]
	v_exp_f32_e32 v44, v44
	v_exp_f32_e32 v45, v45
	v_exp_f32_e32 v46, v46
	v_exp_f32_e32 v47, v47
	v_exp_f32_e32 v36, v36
	v_exp_f32_e32 v37, v37
	v_exp_f32_e32 v38, v38
	v_exp_f32_e32 v39, v39
	v_pk_mul_f32 v[40:41], v[40:41], v[188:189] op_sel:[0,1] op_sel_hi:[1,1]
	v_pk_mul_f32 v[42:43], v[42:43], v[188:189] op_sel:[0,1] op_sel_hi:[1,1]
	v_pk_mul_f32 v[32:33], v[32:33], v[188:189] op_sel:[0,1] op_sel_hi:[1,1]
	v_pk_mul_f32 v[34:35], v[34:35], v[188:189] op_sel:[0,1] op_sel_hi:[1,1]
	v_pk_add_f32 v[44:45], v[44:45], 1.0 op_sel_hi:[1,0]
	v_pk_add_f32 v[46:47], v[46:47], 1.0 op_sel_hi:[1,0]
	v_pk_add_f32 v[36:37], v[36:37], 1.0 op_sel_hi:[1,0]
	v_pk_add_f32 v[38:39], v[38:39], 1.0 op_sel_hi:[1,0]
	v_rcp_f32_e32 v44, v44
	v_rcp_f32_e32 v45, v45
	v_rcp_f32_e32 v46, v46
	v_rcp_f32_e32 v47, v47
	v_rcp_f32_e32 v36, v36
	v_rcp_f32_e32 v37, v37
	v_rcp_f32_e32 v38, v38
	v_rcp_f32_e32 v39, v39
	v_mad_i64_i32 v[208:209], s[4:5], v152, s68, v[220:221]
	v_lshl_add_u64 v[208:209], v[208:209], 0, v[250:251]
	v_pk_mul_f32 v[40:41], v[40:41], v[44:45]
	v_pk_mul_f32 v[42:43], v[42:43], v[46:47]
	v_pk_mul_f32 v[32:33], v[32:33], v[36:37]
	v_pk_mul_f32 v[34:35], v[34:35], v[38:39]
	v_cvt_pk_bf16_f32 v44, v40, v41
	v_cvt_pk_bf16_f32 v45, v42, v43
	v_cvt_pk_bf16_f32 v46, v32, v33
	v_cvt_pk_bf16_f32 v47, v34, v35
	global_store_dwordx4 v[208:209], v[44:47], off sc1
	v_pk_mul_f32 v[28:29], v[28:29], v[190:191] op_sel_hi:[1,0]
	v_pk_mul_f32 v[30:31], v[30:31], v[190:191] op_sel_hi:[1,0]
	v_pk_mul_f32 v[20:21], v[20:21], v[190:191] op_sel_hi:[1,0]
	v_pk_mul_f32 v[22:23], v[22:23], v[190:191] op_sel_hi:[1,0]
	v_exp_f32_e32 v28, v28
	v_exp_f32_e32 v29, v29
	v_exp_f32_e32 v30, v30
	v_exp_f32_e32 v31, v31
	v_exp_f32_e32 v20, v20
	v_exp_f32_e32 v21, v21
	v_exp_f32_e32 v22, v22
	v_exp_f32_e32 v23, v23
	v_pk_mul_f32 v[24:25], v[24:25], v[190:191] op_sel:[0,1] op_sel_hi:[1,1]
	v_pk_mul_f32 v[26:27], v[26:27], v[190:191] op_sel:[0,1] op_sel_hi:[1,1]
	v_pk_mul_f32 v[16:17], v[16:17], v[190:191] op_sel:[0,1] op_sel_hi:[1,1]
	v_pk_mul_f32 v[18:19], v[18:19], v[190:191] op_sel:[0,1] op_sel_hi:[1,1]
	v_pk_add_f32 v[28:29], v[28:29], 1.0 op_sel_hi:[1,0]
	v_pk_add_f32 v[30:31], v[30:31], 1.0 op_sel_hi:[1,0]
	v_pk_add_f32 v[20:21], v[20:21], 1.0 op_sel_hi:[1,0]
	v_pk_add_f32 v[22:23], v[22:23], 1.0 op_sel_hi:[1,0]
	v_rcp_f32_e32 v28, v28
	v_rcp_f32_e32 v29, v29
	v_rcp_f32_e32 v30, v30
	v_rcp_f32_e32 v31, v31
	v_rcp_f32_e32 v20, v20
	v_rcp_f32_e32 v21, v21
	v_rcp_f32_e32 v22, v22
	v_rcp_f32_e32 v23, v23
	v_mad_i64_i32 v[208:209], s[4:5], v150, s68, v[220:221]
	v_lshl_add_u64 v[208:209], v[208:209], 0, v[250:251]
	v_pk_mul_f32 v[24:25], v[24:25], v[28:29]
	v_pk_mul_f32 v[26:27], v[26:27], v[30:31]
	v_pk_mul_f32 v[16:17], v[16:17], v[20:21]
	v_pk_mul_f32 v[18:19], v[18:19], v[22:23]
	v_cvt_pk_bf16_f32 v28, v24, v25
	v_cvt_pk_bf16_f32 v29, v26, v27
	v_cvt_pk_bf16_f32 v30, v16, v17
	v_cvt_pk_bf16_f32 v31, v18, v19
	global_store_dwordx4 v[208:209], v[28:31], off sc1
	v_pk_mul_f32 v[12:13], v[12:13], v[204:205] op_sel_hi:[1,0]
	v_pk_mul_f32 v[14:15], v[14:15], v[204:205] op_sel_hi:[1,0]
	v_pk_mul_f32 v[4:5], v[4:5], v[204:205] op_sel_hi:[1,0]
	v_pk_mul_f32 v[6:7], v[6:7], v[204:205] op_sel_hi:[1,0]
	v_exp_f32_e32 v12, v12
	v_exp_f32_e32 v13, v13
	v_exp_f32_e32 v14, v14
	v_exp_f32_e32 v15, v15
	v_exp_f32_e32 v4, v4
	v_exp_f32_e32 v5, v5
	v_exp_f32_e32 v6, v6
	v_exp_f32_e32 v7, v7
	v_pk_mul_f32 v[8:9], v[8:9], v[204:205] op_sel:[0,1] op_sel_hi:[1,1]
	v_pk_mul_f32 v[10:11], v[10:11], v[204:205] op_sel:[0,1] op_sel_hi:[1,1]
	v_pk_mul_f32 v[0:1], v[0:1], v[204:205] op_sel:[0,1] op_sel_hi:[1,1]
	v_pk_mul_f32 v[2:3], v[2:3], v[204:205] op_sel:[0,1] op_sel_hi:[1,1]
	v_pk_add_f32 v[12:13], v[12:13], 1.0 op_sel_hi:[1,0]
	v_pk_add_f32 v[14:15], v[14:15], 1.0 op_sel_hi:[1,0]
	v_pk_add_f32 v[4:5], v[4:5], 1.0 op_sel_hi:[1,0]
	v_pk_add_f32 v[6:7], v[6:7], 1.0 op_sel_hi:[1,0]
	v_rcp_f32_e32 v12, v12
	v_rcp_f32_e32 v13, v13
	v_rcp_f32_e32 v14, v14
	v_rcp_f32_e32 v15, v15
	v_rcp_f32_e32 v4, v4
	v_rcp_f32_e32 v5, v5
	v_rcp_f32_e32 v6, v6
	v_rcp_f32_e32 v7, v7
	v_mad_i64_i32 v[208:209], s[4:5], v148, s68, v[220:221]
	v_lshl_add_u64 v[208:209], v[208:209], 0, v[250:251]
	v_pk_mul_f32 v[8:9], v[8:9], v[12:13]
	v_pk_mul_f32 v[10:11], v[10:11], v[14:15]
	v_pk_mul_f32 v[0:1], v[0:1], v[4:5]
	v_pk_mul_f32 v[2:3], v[2:3], v[6:7]
	v_cvt_pk_bf16_f32 v12, v8, v9
	v_cvt_pk_bf16_f32 v13, v10, v11
	v_cvt_pk_bf16_f32 v14, v0, v1
	v_cvt_pk_bf16_f32 v15, v2, v3
	global_store_dwordx4 v[208:209], v[12:15], off sc1
	s_cbranch_vccnz .LBB0_255
	s_andn2_b64 vcc, exec, s[16:17]
	s_cbranch_vccnz .LBB0_254
	s_barrier
	s_branch .LBB0_254

; __device__ __forceinline__ unsigned cvt_pk_bf16(float lo, float hi) { unsigned r; asm volatile("v_cvt_pk_bf16_f32 %0, %1, %2" : "=v"(r) : "v"(lo), "v"(hi)); return r; }
; __device__ __forceinline__ float fast_rcp(float x) { return __builtin_amdgcn_rcpf(x); }
; __device__ __forceinline__ unsigned cvt_pk_bf16(float lo, float hi) { const f32x2 v = {lo, hi}; const bf16x2_t b = __builtin_convertvector(v, bf16x2_t); return __builtin_bit_cast(unsigned, b); }
;     __device__ __forceinline__ void operator()(const f32x4 (&acc)[2][2][4][2], const Unit& u, int wr, int wc, int fr, int fq) const {
;         const int row0 = u.pm * BM + wr * 64 + fr, col0 = u.pn * HALF + wc * 32 + 8 * fq;
;         float rsv[2][4]; row_rs8(SS, row0, fq, rsv);
; #pragma unroll
;         for (int ai = 0; ai < 2; ++ai)
; #pragma unroll
;             for (int m = 0; m < 4; ++m) {
;                 const int r = row0 + ai * HALF + m * 16; const float rs = rsv[ai][m], nrs = rs * -1.4426950408889634f, rs2 = rs * rs;
;                 float o[8];
; #pragma unroll
;                 for (int n = 0; n < 2; ++n) {
;                     const f32x4 t = acc[ai][0][m][n] * nrs, p = (acc[ai][0][m][n] * acc[ai][1][m][n]) * rs2;
; #pragma unroll
;                     for (int j = 0; j < 4; ++j) o[4 * n + j] = p[j] * fast_rcp(1.0f + __builtin_amdgcn_exp2f(t[j]));
;                 }
;                 u32x4 w; w.x = cvt_pk_bf16(o[0], o[1]); w.y = cvt_pk_bf16(o[2], o[3]); w.z = cvt_pk_bf16(o[4], o[5]); w.w = cvt_pk_bf16(o[6], o[7]);
;                 *(u32x4*)(O + (size_t)r * ldo + col0) = w;
;             }
.Lrs_reuse_p6:
	v_pk_mul_f32 v[124:125], v[124:125], v[120:121]
	v_pk_mul_f32 v[126:127], v[126:127], v[122:123]
	v_pk_mul_f32 v[112:113], v[112:113], v[116:117]
	v_pk_mul_f32 v[114:115], v[114:115], v[118:119]
	v_pk_mul_f32 v[104:105], v[104:105], v[108:109]
	v_pk_mul_f32 v[106:107], v[106:107], v[110:111]
	v_pk_mul_f32 v[96:97], v[96:97], v[100:101]
	v_pk_mul_f32 v[98:99], v[98:99], v[102:103]
	v_pk_mul_f32 v[88:89], v[88:89], v[92:93]
	v_pk_mul_f32 v[90:91], v[90:91], v[94:95]
	v_pk_mul_f32 v[80:81], v[80:81], v[84:85]
	v_pk_mul_f32 v[82:83], v[82:83], v[86:87]
	v_pk_mul_f32 v[72:73], v[72:73], v[76:77]
	v_pk_mul_f32 v[74:75], v[74:75], v[78:79]
	v_pk_mul_f32 v[64:65], v[64:65], v[68:69]
	v_pk_mul_f32 v[66:67], v[66:67], v[70:71]
	v_pk_mul_f32 v[56:57], v[56:57], v[60:61]
	v_pk_mul_f32 v[58:59], v[58:59], v[62:63]
	v_pk_mul_f32 v[48:49], v[48:49], v[52:53]
	v_pk_mul_f32 v[50:51], v[50:51], v[54:55]
	v_pk_mul_f32 v[40:41], v[40:41], v[44:45]
	v_pk_mul_f32 v[42:43], v[42:43], v[46:47]
	v_pk_mul_f32 v[32:33], v[32:33], v[36:37]
	v_pk_mul_f32 v[34:35], v[34:35], v[38:39]
	v_pk_mul_f32 v[24:25], v[24:25], v[28:29]
	v_pk_mul_f32 v[26:27], v[26:27], v[30:31]
	v_pk_mul_f32 v[16:17], v[16:17], v[20:21]
	v_pk_mul_f32 v[18:19], v[18:19], v[22:23]
	v_pk_mul_f32 v[8:9], v[8:9], v[12:13]
	v_pk_mul_f32 v[10:11], v[10:11], v[14:15]
	v_pk_mul_f32 v[0:1], v[0:1], v[4:5]
	v_pk_mul_f32 v[2:3], v[2:3], v[6:7]
	v_mul_f32_e32 v230, 0xbfb8aa3b, v242
	v_mul_f32_e32 v231, v242, v242
	v_mul_f32_e32 v232, 0xbfb8aa3b, v243
	v_mul_f32_e32 v233, v243, v243
	v_mul_f32_e32 v234, 0xbfb8aa3b, v244
	v_mul_f32_e32 v235, v244, v244
	v_mul_f32_e32 v184, 0xbfb8aa3b, v245
	v_mul_f32_e32 v185, v245, v245
	v_mul_f32_e32 v186, 0xbfb8aa3b, v246
	v_mul_f32_e32 v187, v246, v246
	v_mul_f32_e32 v188, 0xbfb8aa3b, v247
	v_mul_f32_e32 v189, v247, v247
	v_mul_f32_e32 v190, 0xbfb8aa3b, v248
	v_mul_f32_e32 v191, v248, v248
	v_mul_f32_e32 v204, 0xbfb8aa3b, v249
	v_mul_f32_e32 v205, v249, v249
	v_pk_mul_f32 v[120:121], v[120:121], v[230:231] op_sel_hi:[1,0]
	v_pk_mul_f32 v[122:123], v[122:123], v[230:231] op_sel_hi:[1,0]
	v_pk_mul_f32 v[116:117], v[116:117], v[230:231] op_sel_hi:[1,0]
	v_pk_mul_f32 v[118:119], v[118:119], v[230:231] op_sel_hi:[1,0]
	v_exp_f32_e32 v120, v120
	v_exp_f32_e32 v121, v121
	v_exp_f32_e32 v122, v122
	v_exp_f32_e32 v123, v123
	v_exp_f32_e32 v116, v116
	v_exp_f32_e32 v117, v117
	v_exp_f32_e32 v118, v118
	v_exp_f32_e32 v119, v119
	v_pk_mul_f32 v[124:125], v[124:125], v[230:231] op_sel:[0,1] op_sel_hi:[1,1]
	v_pk_mul_f32 v[126:127], v[126:127], v[230:231] op_sel:[0,1] op_sel_hi:[1,1]
	v_pk_mul_f32 v[112:113], v[112:113], v[230:231] op_sel:[0,1] op_sel_hi:[1,1]
	v_pk_mul_f32 v[114:115], v[114:115], v[230:231] op_sel:[0,1] op_sel_hi:[1,1]
	v_pk_add_f32 v[120:121], v[120:121], 1.0 op_sel_hi:[1,0]
	v_pk_add_f32 v[122:123], v[122:123], 1.0 op_sel_hi:[1,0]
	v_pk_add_f32 v[116:117], v[116:117], 1.0 op_sel_hi:[1,0]
	v_pk_add_f32 v[118:119], v[118:119], 1.0 op_sel_hi:[1,0]
	v_rcp_f32_e32 v120, v120
	v_rcp_f32_e32 v121, v121
	v_rcp_f32_e32 v122, v122
	v_rcp_f32_e32 v123, v123
	v_rcp_f32_e32 v116, v116
	v_rcp_f32_e32 v117, v117
	v_rcp_f32_e32 v118, v118
	v_rcp_f32_e32 v119, v119
	v_mad_i64_i32 v[208:209], s[4:5], v162, s67, v[220:221]
	v_lshl_add_u64 v[208:209], v[208:209], 0, v[250:251]
	v_pk_mul_f32 v[124:125], v[124:125], v[120:121]
	v_pk_mul_f32 v[126:127], v[126:127], v[122:123]
	v_pk_mul_f32 v[112:113], v[112:113], v[116:117]
	v_pk_mul_f32 v[114:115], v[114:115], v[118:119]
	v_cvt_pk_bf16_f32 v120, v124, v125
	v_cvt_pk_bf16_f32 v121, v126, v127
	v_cvt_pk_bf16_f32 v122, v112, v113
	v_cvt_pk_bf16_f32 v123, v114, v115
	global_store_dwordx4 v[208:209], v[120:123], off sc1
	v_pk_mul_f32 v[108:109], v[108:109], v[232:233] op_sel_hi:[1,0]
	v_pk_mul_f32 v[110:111], v[110:111], v[232:233] op_sel_hi:[1,0]
	v_pk_mul_f32 v[100:101], v[100:101], v[232:233] op_sel_hi:[1,0]
	v_pk_mul_f32 v[102:103], v[102:103], v[232:233] op_sel_hi:[1,0]
	v_exp_f32_e32 v108, v108
	v_exp_f32_e32 v109, v109
	v_exp_f32_e32 v110, v110
	v_exp_f32_e32 v111, v111
	v_exp_f32_e32 v100, v100
	v_exp_f32_e32 v101, v101
	v_exp_f32_e32 v102, v102
	v_exp_f32_e32 v103, v103
	v_pk_mul_f32 v[104:105], v[104:105], v[232:233] op_sel:[0,1] op_sel_hi:[1,1]
	v_pk_mul_f32 v[106:107], v[106:107], v[232:233] op_sel:[0,1] op_sel_hi:[1,1]
	v_pk_mul_f32 v[96:97], v[96:97], v[232:233] op_sel:[0,1] op_sel_hi:[1,1]
	v_pk_mul_f32 v[98:99], v[98:99], v[232:233] op_sel:[0,1] op_sel_hi:[1,1]
	v_pk_add_f32 v[108:109], v[108:109], 1.0 op_sel_hi:[1,0]
	v_pk_add_f32 v[110:111], v[110:111], 1.0 op_sel_hi:[1,0]
	v_pk_add_f32 v[100:101], v[100:101], 1.0 op_sel_hi:[1,0]
	v_pk_add_f32 v[102:103], v[102:103], 1.0 op_sel_hi:[1,0]
	v_rcp_f32_e32 v108, v108
	v_rcp_f32_e32 v109, v109
	v_rcp_f32_e32 v110, v110
	v_rcp_f32_e32 v111, v111
	v_rcp_f32_e32 v100, v100
	v_rcp_f32_e32 v101, v101
	v_rcp_f32_e32 v102, v102
	v_rcp_f32_e32 v103, v103
	v_mad_i64_i32 v[208:209], s[4:5], v160, s67, v[220:221]
	v_lshl_add_u64 v[208:209], v[208:209], 0, v[250:251]
	v_pk_mul_f32 v[104:105], v[104:105], v[108:109]
	v_pk_mul_f32 v[106:107], v[106:107], v[110:111]
	v_pk_mul_f32 v[96:97], v[96:97], v[100:101]
	v_pk_mul_f32 v[98:99], v[98:99], v[102:103]
	v_cvt_pk_bf16_f32 v108, v104, v105
	v_cvt_pk_bf16_f32 v109, v106, v107
	v_cvt_pk_bf16_f32 v110, v96, v97
	v_cvt_pk_bf16_f32 v111, v98, v99
	global_store_dwordx4 v[208:209], v[108:111], off sc1
	v_pk_mul_f32 v[92:93], v[92:93], v[234:235] op_sel_hi:[1,0]
	v_pk_mul_f32 v[94:95], v[94:95], v[234:235] op_sel_hi:[1,0]
	v_pk_mul_f32 v[84:85], v[84:85], v[234:235] op_sel_hi:[1,0]
	v_pk_mul_f32 v[86:87], v[86:87], v[234:235] op_sel_hi:[1,0]
; __device__ __forceinline__ unsigned cvt_pk_bf16(float lo, float hi) { unsigned r; asm volatile("v_cvt_pk_bf16_f32 %0, %1, %2" : "=v"(r) : "v"(lo), "v"(hi)); return r; }
; __device__ __forceinline__ float fast_rcp(float x) { return __builtin_amdgcn_rcpf(x); }
; __device__ __forceinline__ unsigned cvt_pk_bf16(float lo, float hi) { const f32x2 v = {lo, hi}; const bf16x2_t b = __builtin_convertvector(v, bf16x2_t); return __builtin_bit_cast(unsigned, b); }
;     __device__ __forceinline__ void operator()(const f32x4 (&acc)[2][2][4][2], const Unit& u, int wr, int wc, int fr, int fq) const {
;         const int row0 = u.pm * BM + wr * 64 + fr, col0 = u.pn * HALF + wc * 32 + 8 * fq;
;         float rsv[2][4]; row_rs8(SS, row0, fq, rsv);
; #pragma unroll
;         for (int ai = 0; ai < 2; ++ai)
; #pragma unroll
;             for (int m = 0; m < 4; ++m) {
;                 const int r = row0 + ai * HALF + m * 16; const float rs = rsv[ai][m], nrs = rs * -1.4426950408889634f, rs2 = rs * rs;
;                 float o[8];
; #pragma unroll
;                 for (int n = 0; n < 2; ++n) {
;                     const f32x4 t = acc[ai][0][m][n] * nrs, p = (acc[ai][0][m][n] * acc[ai][1][m][n]) * rs2;
; #pragma unroll
;                     for (int j = 0; j < 4; ++j) o[4 * n + j] = p[j] * fast_rcp(1.0f + __builtin_amdgcn_exp2f(t[j]));
;                 }
;                 u32x4 w; w.x = cvt_pk_bf16(o[0], o[1]); w.y = cvt_pk_bf16(o[2], o[3]); w.z = cvt_pk_bf16(o[4], o[5]); w.w = cvt_pk_bf16(o[6], o[7]);
;                 *(u32x4*)(O + (size_t)r * ldo + col0) = w;
;             }
	v_exp_f32_e32 v92, v92
	v_exp_f32_e32 v93, v93
	v_exp_f32_e32 v94, v94
	v_exp_f32_e32 v95, v95
	v_exp_f32_e32 v84, v84
	v_exp_f32_e32 v85, v85
	v_exp_f32_e32 v86, v86
	v_exp_f32_e32 v87, v87
	v_pk_mul_f32 v[88:89], v[88:89], v[234:235] op_sel:[0,1] op_sel_hi:[1,1]
	v_pk_mul_f32 v[90:91], v[90:91], v[234:235] op_sel:[0,1] op_sel_hi:[1,1]
	v_pk_mul_f32 v[80:81], v[80:81], v[234:235] op_sel:[0,1] op_sel_hi:[1,1]
	v_pk_mul_f32 v[82:83], v[82:83], v[234:235] op_sel:[0,1] op_sel_hi:[1,1]
	v_pk_add_f32 v[92:93], v[92:93], 1.0 op_sel_hi:[1,0]
	v_pk_add_f32 v[94:95], v[94:95], 1.0 op_sel_hi:[1,0]
	v_pk_add_f32 v[84:85], v[84:85], 1.0 op_sel_hi:[1,0]
	v_pk_add_f32 v[86:87], v[86:87], 1.0 op_sel_hi:[1,0]
	v_rcp_f32_e32 v92, v92
	v_rcp_f32_e32 v93, v93
	v_rcp_f32_e32 v94, v94
	v_rcp_f32_e32 v95, v95
	v_rcp_f32_e32 v84, v84
	v_rcp_f32_e32 v85, v85
	v_rcp_f32_e32 v86, v86
	v_rcp_f32_e32 v87, v87
	v_mad_i64_i32 v[208:209], s[4:5], v158, s67, v[220:221]
	v_lshl_add_u64 v[208:209], v[208:209], 0, v[250:251]
	v_pk_mul_f32 v[88:89], v[88:89], v[92:93]
	v_pk_mul_f32 v[90:91], v[90:91], v[94:95]
	v_pk_mul_f32 v[80:81], v[80:81], v[84:85]
	v_pk_mul_f32 v[82:83], v[82:83], v[86:87]
	v_cvt_pk_bf16_f32 v92, v88, v89
	v_cvt_pk_bf16_f32 v93, v90, v91
	v_cvt_pk_bf16_f32 v94, v80, v81
	v_cvt_pk_bf16_f32 v95, v82, v83
	global_store_dwordx4 v[208:209], v[92:95], off sc1
	v_pk_mul_f32 v[76:77], v[76:77], v[184:185] op_sel_hi:[1,0]
	v_pk_mul_f32 v[78:79], v[78:79], v[184:185] op_sel_hi:[1,0]
	v_pk_mul_f32 v[68:69], v[68:69], v[184:185] op_sel_hi:[1,0]
	v_pk_mul_f32 v[70:71], v[70:71], v[184:185] op_sel_hi:[1,0]
	v_exp_f32_e32 v76, v76
	v_exp_f32_e32 v77, v77
	v_exp_f32_e32 v78, v78
	v_exp_f32_e32 v79, v79
	v_exp_f32_e32 v68, v68
	v_exp_f32_e32 v69, v69
	v_exp_f32_e32 v70, v70
	v_exp_f32_e32 v71, v71
	v_pk_mul_f32 v[72:73], v[72:73], v[184:185] op_sel:[0,1] op_sel_hi:[1,1]
	v_pk_mul_f32 v[74:75], v[74:75], v[184:185] op_sel:[0,1] op_sel_hi:[1,1]
	v_pk_mul_f32 v[64:65], v[64:65], v[184:185] op_sel:[0,1] op_sel_hi:[1,1]
	v_pk_mul_f32 v[66:67], v[66:67], v[184:185] op_sel:[0,1] op_sel_hi:[1,1]
	v_pk_add_f32 v[76:77], v[76:77], 1.0 op_sel_hi:[1,0]
	v_pk_add_f32 v[78:79], v[78:79], 1.0 op_sel_hi:[1,0]
	v_pk_add_f32 v[68:69], v[68:69], 1.0 op_sel_hi:[1,0]
	v_pk_add_f32 v[70:71], v[70:71], 1.0 op_sel_hi:[1,0]
	v_rcp_f32_e32 v76, v76
	v_rcp_f32_e32 v77, v77
	v_rcp_f32_e32 v78, v78
	v_rcp_f32_e32 v79, v79
	v_rcp_f32_e32 v68, v68
	v_rcp_f32_e32 v69, v69
	v_rcp_f32_e32 v70, v70
	v_rcp_f32_e32 v71, v71
	v_mad_i64_i32 v[208:209], s[4:5], v156, s67, v[220:221]
	v_lshl_add_u64 v[208:209], v[208:209], 0, v[250:251]
	v_pk_mul_f32 v[72:73], v[72:73], v[76:77]
	v_pk_mul_f32 v[74:75], v[74:75], v[78:79]
	v_pk_mul_f32 v[64:65], v[64:65], v[68:69]
	v_pk_mul_f32 v[66:67], v[66:67], v[70:71]
	v_cvt_pk_bf16_f32 v76, v72, v73
	v_cvt_pk_bf16_f32 v77, v74, v75
	v_cvt_pk_bf16_f32 v78, v64, v65
	v_cvt_pk_bf16_f32 v79, v66, v67
	global_store_dwordx4 v[208:209], v[76:79], off sc1
	v_pk_mul_f32 v[60:61], v[60:61], v[186:187] op_sel_hi:[1,0]
	v_pk_mul_f32 v[62:63], v[62:63], v[186:187] op_sel_hi:[1,0]
	v_pk_mul_f32 v[52:53], v[52:53], v[186:187] op_sel_hi:[1,0]
	v_pk_mul_f32 v[54:55], v[54:55], v[186:187] op_sel_hi:[1,0]
	v_exp_f32_e32 v60, v60
	v_exp_f32_e32 v61, v61
	v_exp_f32_e32 v62, v62
	v_exp_f32_e32 v63, v63
	v_exp_f32_e32 v52, v52
	v_exp_f32_e32 v53, v53
	v_exp_f32_e32 v54, v54
	v_exp_f32_e32 v55, v55
	v_pk_mul_f32 v[56:57], v[56:57], v[186:187] op_sel:[0,1] op_sel_hi:[1,1]
	v_pk_mul_f32 v[58:59], v[58:59], v[186:187] op_sel:[0,1] op_sel_hi:[1,1]
	v_pk_mul_f32 v[48:49], v[48:49], v[186:187] op_sel:[0,1] op_sel_hi:[1,1]
	v_pk_mul_f32 v[50:51], v[50:51], v[186:187] op_sel:[0,1] op_sel_hi:[1,1]
	v_pk_add_f32 v[60:61], v[60:61], 1.0 op_sel_hi:[1,0]
	v_pk_add_f32 v[62:63], v[62:63], 1.0 op_sel_hi:[1,0]
	v_pk_add_f32 v[52:53], v[52:53], 1.0 op_sel_hi:[1,0]
	v_pk_add_f32 v[54:55], v[54:55], 1.0 op_sel_hi:[1,0]
	v_rcp_f32_e32 v60, v60
	v_rcp_f32_e32 v61, v61
	v_rcp_f32_e32 v62, v62
	v_rcp_f32_e32 v63, v63
	v_rcp_f32_e32 v52, v52
	v_rcp_f32_e32 v53, v53
	v_rcp_f32_e32 v54, v54
	v_rcp_f32_e32 v55, v55
	v_mad_i64_i32 v[208:209], s[4:5], v154, s67, v[220:221]
	v_lshl_add_u64 v[208:209], v[208:209], 0, v[250:251]
	v_pk_mul_f32 v[56:57], v[56:57], v[60:61]
	v_pk_mul_f32 v[58:59], v[58:59], v[62:63]
	v_pk_mul_f32 v[48:49], v[48:49], v[52:53]
	v_pk_mul_f32 v[50:51], v[50:51], v[54:55]
	v_cvt_pk_bf16_f32 v60, v56, v57
	v_cvt_pk_bf16_f32 v61, v58, v59
	v_cvt_pk_bf16_f32 v62, v48, v49
	v_cvt_pk_bf16_f32 v63, v50, v51
	global_store_dwordx4 v[208:209], v[60:63], off sc1
	v_pk_mul_f32 v[44:45], v[44:45], v[188:189] op_sel_hi:[1,0]
	v_pk_mul_f32 v[46:47], v[46:47], v[188:189] op_sel_hi:[1,0]
; __device__ __forceinline__ unsigned cvt_pk_bf16(float lo, float hi) { unsigned r; asm volatile("v_cvt_pk_bf16_f32 %0, %1, %2" : "=v"(r) : "v"(lo), "v"(hi)); return r; }
; __device__ __forceinline__ float fast_rcp(float x) { return __builtin_amdgcn_rcpf(x); }
; #define PG8_BAR __builtin_amdgcn_s_barrier()
; __device__ __forceinline__ unsigned cvt_pk_bf16(float lo, float hi) { const f32x2 v = {lo, hi}; const bf16x2_t b = __builtin_convertvector(v, bf16x2_t); return __builtin_bit_cast(unsigned, b); }
;     __device__ __forceinline__ void operator()(const f32x4 (&acc)[2][2][4][2], const Unit& u, int wr, int wc, int fr, int fq) const {
;         const int row0 = u.pm * BM + wr * 64 + fr, col0 = u.pn * HALF + wc * 32 + 8 * fq;
;         float rsv[2][4]; row_rs8(SS, row0, fq, rsv);
; #pragma unroll
;         for (int ai = 0; ai < 2; ++ai)
; #pragma unroll
;             for (int m = 0; m < 4; ++m) {
;                 const int r = row0 + ai * HALF + m * 16; const float rs = rsv[ai][m], nrs = rs * -1.4426950408889634f, rs2 = rs * rs;
;                 float o[8];
; #pragma unroll
;                 for (int n = 0; n < 2; ++n) {
;                     const f32x4 t = acc[ai][0][m][n] * nrs, p = (acc[ai][0][m][n] * acc[ai][1][m][n]) * rs2;
; #pragma unroll
;                     for (int j = 0; j < 4; ++j) o[4 * n + j] = p[j] * fast_rcp(1.0f + __builtin_amdgcn_exp2f(t[j]));
;                 }
;                 u32x4 w; w.x = cvt_pk_bf16(o[0], o[1]); w.y = cvt_pk_bf16(o[2], o[3]); w.z = cvt_pk_bf16(o[4], o[5]); w.w = cvt_pk_bf16(o[6], o[7]);
;                 *(u32x4*)(O + (size_t)r * ldo + col0) = w;
;             }
; template <class Epi, class Sched, bool ALIGN_EPI = false, bool SP2 = false>
; __device__ __forceinline__ void gemm_phase(PG8_LAS unsigned char* lds, const Gemm g, const Sched& S, const Epi& E) {
;     ...
;         if (!has_next) break;
; #pragma unroll
;         for (int a = 0; a < 2; ++a)
; #pragma unroll
;             for (int b = 0; b < 2; ++b)
; #pragma unroll
;                 for (int m = 0; m < 4; ++m)
; #pragma unroll
;                     for (int n = 0; n < 2; ++n) acc[a][b][m][n] = (f32x4){0.f, 0.f, 0.f, 0.f};
;         cur = nxt; cA = nA; cB = nB; ++ui;
;         if constexpr (ALIGN_EPI) { if (wr == 1) PG8_BAR; }
	v_pk_mul_f32 v[36:37], v[36:37], v[188:189] op_sel_hi:[1,0]
	v_pk_mul_f32 v[38:39], v[38:39], v[188:189] op_sel_hi:[1,0]
	v_exp_f32_e32 v44, v44
	v_exp_f32_e32 v45, v45
	v_exp_f32_e32 v46, v46
	v_exp_f32_e32 v47, v47
	v_exp_f32_e32 v36, v36
	v_exp_f32_e32 v37, v37
	v_exp_f32_e32 v38, v38
	v_exp_f32_e32 v39, v39
	v_pk_mul_f32 v[40:41], v[40:41], v[188:189] op_sel:[0,1] op_sel_hi:[1,1]
	v_pk_mul_f32 v[42:43], v[42:43], v[188:189] op_sel:[0,1] op_sel_hi:[1,1]
	v_pk_mul_f32 v[32:33], v[32:33], v[188:189] op_sel:[0,1] op_sel_hi:[1,1]
	v_pk_mul_f32 v[34:35], v[34:35], v[188:189] op_sel:[0,1] op_sel_hi:[1,1]
	v_pk_add_f32 v[44:45], v[44:45], 1.0 op_sel_hi:[1,0]
	v_pk_add_f32 v[46:47], v[46:47], 1.0 op_sel_hi:[1,0]
	v_pk_add_f32 v[36:37], v[36:37], 1.0 op_sel_hi:[1,0]
	v_pk_add_f32 v[38:39], v[38:39], 1.0 op_sel_hi:[1,0]
	v_rcp_f32_e32 v44, v44
	v_rcp_f32_e32 v45, v45
	v_rcp_f32_e32 v46, v46
	v_rcp_f32_e32 v47, v47
	v_rcp_f32_e32 v36, v36
	v_rcp_f32_e32 v37, v37
	v_rcp_f32_e32 v38, v38
	v_rcp_f32_e32 v39, v39
	v_mad_i64_i32 v[208:209], s[4:5], v152, s67, v[220:221]
	v_lshl_add_u64 v[208:209], v[208:209], 0, v[250:251]
	v_pk_mul_f32 v[40:41], v[40:41], v[44:45]
	v_pk_mul_f32 v[42:43], v[42:43], v[46:47]
	v_pk_mul_f32 v[32:33], v[32:33], v[36:37]
	v_pk_mul_f32 v[34:35], v[34:35], v[38:39]
	v_cvt_pk_bf16_f32 v44, v40, v41
	v_cvt_pk_bf16_f32 v45, v42, v43
	v_cvt_pk_bf16_f32 v46, v32, v33
	v_cvt_pk_bf16_f32 v47, v34, v35
	global_store_dwordx4 v[208:209], v[44:47], off sc1
	v_pk_mul_f32 v[28:29], v[28:29], v[190:191] op_sel_hi:[1,0]
	v_pk_mul_f32 v[30:31], v[30:31], v[190:191] op_sel_hi:[1,0]
	v_pk_mul_f32 v[20:21], v[20:21], v[190:191] op_sel_hi:[1,0]
	v_pk_mul_f32 v[22:23], v[22:23], v[190:191] op_sel_hi:[1,0]
	v_exp_f32_e32 v28, v28
	v_exp_f32_e32 v29, v29
	v_exp_f32_e32 v30, v30
	v_exp_f32_e32 v31, v31
	v_exp_f32_e32 v20, v20
	v_exp_f32_e32 v21, v21
	v_exp_f32_e32 v22, v22
	v_exp_f32_e32 v23, v23
	v_pk_mul_f32 v[24:25], v[24:25], v[190:191] op_sel:[0,1] op_sel_hi:[1,1]
	v_pk_mul_f32 v[26:27], v[26:27], v[190:191] op_sel:[0,1] op_sel_hi:[1,1]
	v_pk_mul_f32 v[16:17], v[16:17], v[190:191] op_sel:[0,1] op_sel_hi:[1,1]
	v_pk_mul_f32 v[18:19], v[18:19], v[190:191] op_sel:[0,1] op_sel_hi:[1,1]
	v_pk_add_f32 v[28:29], v[28:29], 1.0 op_sel_hi:[1,0]
	v_pk_add_f32 v[30:31], v[30:31], 1.0 op_sel_hi:[1,0]
	v_pk_add_f32 v[20:21], v[20:21], 1.0 op_sel_hi:[1,0]
	v_pk_add_f32 v[22:23], v[22:23], 1.0 op_sel_hi:[1,0]
	v_rcp_f32_e32 v28, v28
	v_rcp_f32_e32 v29, v29
	v_rcp_f32_e32 v30, v30
	v_rcp_f32_e32 v31, v31
	v_rcp_f32_e32 v20, v20
	v_rcp_f32_e32 v21, v21
	v_rcp_f32_e32 v22, v22
	v_rcp_f32_e32 v23, v23
	v_mad_i64_i32 v[208:209], s[4:5], v150, s67, v[220:221]
	v_lshl_add_u64 v[208:209], v[208:209], 0, v[250:251]
	v_pk_mul_f32 v[24:25], v[24:25], v[28:29]
	v_pk_mul_f32 v[26:27], v[26:27], v[30:31]
	v_pk_mul_f32 v[16:17], v[16:17], v[20:21]
	v_pk_mul_f32 v[18:19], v[18:19], v[22:23]
	v_cvt_pk_bf16_f32 v28, v24, v25
	v_cvt_pk_bf16_f32 v29, v26, v27
	v_cvt_pk_bf16_f32 v30, v16, v17
	v_cvt_pk_bf16_f32 v31, v18, v19
	global_store_dwordx4 v[208:209], v[28:31], off sc1
	v_pk_mul_f32 v[12:13], v[12:13], v[204:205] op_sel_hi:[1,0]
	v_pk_mul_f32 v[14:15], v[14:15], v[204:205] op_sel_hi:[1,0]
	v_pk_mul_f32 v[4:5], v[4:5], v[204:205] op_sel_hi:[1,0]
	v_pk_mul_f32 v[6:7], v[6:7], v[204:205] op_sel_hi:[1,0]
	v_exp_f32_e32 v12, v12
	v_exp_f32_e32 v13, v13
	v_exp_f32_e32 v14, v14
	v_exp_f32_e32 v15, v15
	v_exp_f32_e32 v4, v4
	v_exp_f32_e32 v5, v5
	v_exp_f32_e32 v6, v6
	v_exp_f32_e32 v7, v7
	v_pk_mul_f32 v[8:9], v[8:9], v[204:205] op_sel:[0,1] op_sel_hi:[1,1]
	v_pk_mul_f32 v[10:11], v[10:11], v[204:205] op_sel:[0,1] op_sel_hi:[1,1]
	v_pk_mul_f32 v[0:1], v[0:1], v[204:205] op_sel:[0,1] op_sel_hi:[1,1]
	v_pk_mul_f32 v[2:3], v[2:3], v[204:205] op_sel:[0,1] op_sel_hi:[1,1]
	v_pk_add_f32 v[12:13], v[12:13], 1.0 op_sel_hi:[1,0]
	v_pk_add_f32 v[14:15], v[14:15], 1.0 op_sel_hi:[1,0]
	v_pk_add_f32 v[4:5], v[4:5], 1.0 op_sel_hi:[1,0]
	v_pk_add_f32 v[6:7], v[6:7], 1.0 op_sel_hi:[1,0]
	v_rcp_f32_e32 v12, v12
	v_rcp_f32_e32 v13, v13
	v_rcp_f32_e32 v14, v14
	v_rcp_f32_e32 v15, v15
	v_rcp_f32_e32 v4, v4
	v_rcp_f32_e32 v5, v5
	v_rcp_f32_e32 v6, v6
	v_rcp_f32_e32 v7, v7
	v_mad_i64_i32 v[208:209], s[4:5], v148, s67, v[220:221]
	v_lshl_add_u64 v[208:209], v[208:209], 0, v[250:251]
	v_pk_mul_f32 v[8:9], v[8:9], v[12:13]
	v_pk_mul_f32 v[10:11], v[10:11], v[14:15]
	v_pk_mul_f32 v[0:1], v[0:1], v[4:5]
	v_pk_mul_f32 v[2:3], v[2:3], v[6:7]
	v_cvt_pk_bf16_f32 v12, v8, v9
	v_cvt_pk_bf16_f32 v13, v10, v11
	v_cvt_pk_bf16_f32 v14, v0, v1
	v_cvt_pk_bf16_f32 v15, v2, v3
	global_store_dwordx4 v[208:209], v[12:15], off sc1
	s_cbranch_vccnz .LBB0_1005
	s_andn2_b64 vcc, exec, s[14:15]
	s_cbranch_vccnz .LBB0_1004
	s_barrier
	s_branch .LBB0_1004
